# P1 K-loop: A-fragment LDS reads software-pipelined into the preceding MFMA block (second fragment set in spare VGPRs, post-block vmcnt waits)
# baseline (speedup 1.0000x reference)
; #define PG8_STAGE(bufoff, gbase, voff) do { _Pragma("unroll") for (int _i = 0; _i < 2; ++_i) \
;         __builtin_amdgcn_global_load_lds((const unsigned*)((const char*)(gbase) + (voff)[_i]), (PG8_LAS unsigned*)(lds + (bufoff) + ldsw + _i * 8192), 16, 0, 0); } while (0)
; #define PG8_LDA(dst, b, h) do { _Pragma("unroll") for (int m = 0; m < 4; ++m) _Pragma("unroll") for (int k = 0; k < 2; ++k) dst[m][k] = *(const PG8_LAS bf16x8*)(lds + PG8_SA(b, h) + aoff + m * 2048 + k * 1024); } while (0)
; #define PG8_LDB(dst, b, h) do { _Pragma("unroll") for (int n = 0; n < 2; ++n) _Pragma("unroll") for (int k = 0; k < 2; ++k) dst[n][k] = *(const PG8_LAS bf16x8*)(lds + PG8_SB(b, h) + boff + n * 2048 + k * 1024); } while (0)
; #define PG8_SCHED __builtin_amdgcn_sched_barrier(0)
; template <class Epi, class Sched, bool ALIGN_EPI = false, bool SP2 = false, bool SPLITK = false>
; __device__ __forceinline__ void gemm_phase(PG8_LAS unsigned char* lds, const Gemm g, const Sched& S, const Epi& E) {
;     ...
;             PG8_LDB(B0, 0, 0); PG8_LDB(B1, 0, 1); PG8_SCHED; PG8_LDA(At, 0, 0); PG8_STAGE(PG8_SA(1, 1), a1 + hstep, voffA);
;     ...
; #pragma unroll
;         for (int a = 0; a < 2; ++a)
; #pragma unroll
;             for (int b = 0; b < 2; ++b)
; #pragma unroll
;                 for (int m = 0; m < 4; ++m)
; #pragma unroll
;                     for (int n = 0; n < 2; ++n) acc[a][b][m][n] = (f32x4){0.f, 0.f, 0.f, 0.f};
;         cur = nxt; cA = nA; cB = nB; ++ui;
.LBB0_164:
	s_ashr_i32 s35, s34, 31
	s_lshl_b64 s[22:23], s[34:35], 19
	s_add_u32 s36, s82, s22
	s_addc_u32 s37, s83, s23
	s_and_b64 s[22:23], s[38:39], exec
	s_cselect_b32 s4, s37, s49
	s_cselect_b32 s12, s36, s48
	s_ashr_i32 s21, s20, 31
	s_lshl_b64 s[22:23], s[20:21], 19
	v_readlane_b32 s21, v255, 45
	s_add_u32 s40, s21, s22
	v_readlane_b32 s21, v255, 46
	s_addc_u32 s41, s21, s23
	s_and_b64 s[22:23], s[38:39], exec
	s_cselect_b32 s21, s41, s47
	s_cselect_b32 s22, s40, s46
	s_add_u32 s54, s48, 0x40080
	s_addc_u32 s55, s49, 0
	s_add_u32 s23, s46, 0x100
	v_mov_b32_e32 v2, 0
	s_addc_u32 s24, s47, 0
	s_mov_b32 s25, -2
	v_mov_b32_e32 v3, v2
	v_mov_b32_e32 v4, v2
	v_mov_b32_e32 v5, v2
	v_mov_b32_e32 v6, v2
	v_mov_b32_e32 v7, v2
	v_mov_b32_e32 v8, v2
	v_mov_b32_e32 v9, v2
	v_mov_b32_e32 v14, v2
	v_mov_b32_e32 v15, v2
	v_mov_b32_e32 v16, v2
	v_mov_b32_e32 v17, v2
	v_mov_b32_e32 v22, v2
	v_mov_b32_e32 v23, v2
	v_mov_b32_e32 v24, v2
	v_mov_b32_e32 v25, v2
	v_mov_b32_e32 v30, v2
	v_mov_b32_e32 v31, v2
	v_mov_b32_e32 v32, v2
	v_mov_b32_e32 v33, v2
	v_mov_b32_e32 v38, v2
	v_mov_b32_e32 v39, v2
	v_mov_b32_e32 v40, v2
	v_mov_b32_e32 v41, v2
	v_mov_b32_e32 v46, v2
	v_mov_b32_e32 v47, v2
	v_mov_b32_e32 v48, v2
	v_mov_b32_e32 v49, v2
	v_mov_b32_e32 v54, v2
	v_mov_b32_e32 v55, v2
	v_mov_b32_e32 v56, v2
	v_mov_b32_e32 v57, v2
	v_mov_b32_e32 v10, v2
	v_mov_b32_e32 v11, v2
	v_mov_b32_e32 v12, v2
	v_mov_b32_e32 v13, v2
	v_mov_b32_e32 v18, v2
	v_mov_b32_e32 v19, v2
	v_mov_b32_e32 v20, v2
	v_mov_b32_e32 v21, v2
	v_mov_b32_e32 v26, v2
	v_mov_b32_e32 v27, v2
	v_mov_b32_e32 v28, v2
	v_mov_b32_e32 v29, v2
	v_mov_b32_e32 v34, v2
	v_mov_b32_e32 v35, v2
	v_mov_b32_e32 v36, v2
	v_mov_b32_e32 v37, v2
	v_mov_b32_e32 v42, v2
	v_mov_b32_e32 v43, v2
	v_mov_b32_e32 v44, v2
	v_mov_b32_e32 v45, v2
	v_mov_b32_e32 v50, v2
	v_mov_b32_e32 v51, v2
	v_mov_b32_e32 v52, v2
	v_mov_b32_e32 v53, v2
	v_mov_b32_e32 v58, v2
	v_mov_b32_e32 v59, v2
	v_mov_b32_e32 v60, v2
	v_mov_b32_e32 v61, v2
	v_mov_b32_e32 v62, v2
	v_mov_b32_e32 v63, v2
	v_mov_b32_e32 v64, v2
	v_mov_b32_e32 v65, v2
	v_mov_b32_e32 v66, v2
	v_mov_b32_e32 v67, v2
	v_mov_b32_e32 v68, v2
	v_mov_b32_e32 v69, v2
	v_mov_b32_e32 v70, v2
	v_mov_b32_e32 v71, v2
	v_mov_b32_e32 v72, v2
	v_mov_b32_e32 v73, v2
	v_mov_b32_e32 v78, v2
	v_mov_b32_e32 v79, v2
	v_mov_b32_e32 v80, v2
	v_mov_b32_e32 v81, v2
	v_mov_b32_e32 v86, v2
	v_mov_b32_e32 v87, v2
	v_mov_b32_e32 v88, v2
	v_mov_b32_e32 v89, v2
	v_mov_b32_e32 v94, v2
	v_mov_b32_e32 v95, v2
	v_mov_b32_e32 v96, v2
	v_mov_b32_e32 v97, v2
	v_mov_b32_e32 v102, v2
	v_mov_b32_e32 v103, v2
	v_mov_b32_e32 v104, v2
	v_mov_b32_e32 v105, v2
	v_mov_b32_e32 v110, v2
	v_mov_b32_e32 v111, v2
	v_mov_b32_e32 v112, v2
	v_mov_b32_e32 v113, v2
	v_mov_b32_e32 v118, v2
	v_mov_b32_e32 v119, v2
	v_mov_b32_e32 v120, v2
	v_mov_b32_e32 v121, v2
	v_mov_b32_e32 v74, v2
	v_mov_b32_e32 v75, v2
	v_mov_b32_e32 v76, v2
	v_mov_b32_e32 v77, v2
	v_mov_b32_e32 v82, v2
	v_mov_b32_e32 v83, v2
	v_mov_b32_e32 v84, v2
	v_mov_b32_e32 v85, v2
	v_mov_b32_e32 v90, v2
	v_mov_b32_e32 v91, v2
	v_mov_b32_e32 v92, v2
	v_mov_b32_e32 v93, v2
	v_mov_b32_e32 v98, v2
	v_mov_b32_e32 v99, v2
	v_mov_b32_e32 v100, v2
	v_mov_b32_e32 v101, v2
	v_mov_b32_e32 v106, v2
	v_mov_b32_e32 v107, v2
	v_mov_b32_e32 v108, v2
	v_mov_b32_e32 v109, v2
	v_mov_b32_e32 v114, v2
	v_mov_b32_e32 v115, v2
	v_mov_b32_e32 v116, v2
	v_mov_b32_e32 v117, v2
	v_mov_b32_e32 v122, v2
	v_mov_b32_e32 v123, v2
	v_mov_b32_e32 v124, v2
	v_mov_b32_e32 v125, v2
	v_mov_b32_e32 v126, v2
	v_mov_b32_e32 v127, v2
	v_mov_b32_e32 v128, v2
	v_mov_b32_e32 v129, v2
	ds_read_b128 v[162:165], v199 offset:0
	ds_read_b128 v[178:181], v199 offset:1024
	ds_read_b128 v[182:185], v199 offset:2048
	ds_read_b128 v[186:189], v199 offset:3072
	ds_read_b128 v[190:193], v199 offset:4096
	ds_read_b128 v[200:203], v199 offset:5120
	ds_read_b128 v[204:207], v199 offset:6144
.LBB0_165:
	s_add_u32 s35, s54, 0xfffc0080
	s_addc_u32 s43, s55, -1
	s_add_i32 s45, 0, 0x10000
	s_cmp_eq_u32 s25, 12
	s_cselect_b32 s49, s4, s43
	s_cselect_b32 s48, s12, s35
	s_cselect_b32 s47, s21, s24
	s_cselect_b32 s46, s22, s23
	s_add_i32 s35, 0, 0x14000
	v_add_u32_e32 v142, s45, v198
	v_add_u32_e32 v158, s35, v198
	ds_read_b128 v[130:133], v142
	ds_read_b128 v[134:137], v142 offset:1024
	ds_read_b128 v[138:141], v142 offset:2048
	ds_read_b128 v[142:145], v142 offset:3072
	ds_read_b128 v[146:149], v158
	ds_read_b128 v[150:153], v158 offset:1024
	ds_read_b128 v[154:157], v158 offset:2048
	ds_read_b128 v[158:161], v158 offset:3072
	s_add_i32 m0, s51, 0xc000
	ds_read_b128 v[208:211], v199 offset:7168
	global_load_lds_dwordx4 v174, s[54:55]
	s_add_i32 m0, s51, 0xe000
	s_nop 0
	global_load_lds_dwordx4 v176, s[54:55]
	s_waitcnt vmcnt(8)
	s_waitcnt lgkmcnt(0)
	s_barrier
; #define PG8_STAGE(bufoff, gbase, voff) do { _Pragma("unroll") for (int _i = 0; _i < 2; ++_i) \
;         __builtin_amdgcn_global_load_lds((const unsigned*)((const char*)(gbase) + (voff)[_i]), (PG8_LAS unsigned*)(lds + (bufoff) + ldsw + _i * 8192), 16, 0, 0); } while (0)
; #define PG8_LDA(dst, b, h) do { _Pragma("unroll") for (int m = 0; m < 4; ++m) _Pragma("unroll") for (int k = 0; k < 2; ++k) dst[m][k] = *(const PG8_LAS bf16x8*)(lds + PG8_SA(b, h) + aoff + m * 2048 + k * 1024); } while (0)
; #define PG8_MMA(ai, bj, At, Bt) do { __builtin_amdgcn_s_setprio(1); _Pragma("unroll") for (int m = 0; m < 4; ++m) _Pragma("unroll") for (int n = 0; n < 2; ++n) _Pragma("unroll") for (int k = 0; k < 2; ++k) \
;         acc[ai][bj][m][n] = __builtin_amdgcn_mfma_f32_16x16x32_bf16(Bt[n][k], At[m][k], acc[ai][bj][m][n], 0, 0, 0); __builtin_amdgcn_s_setprio(0); } while (0)
; #define PG8_WAIT_V(n) asm volatile("s_waitcnt vmcnt(" #n ")" ::: "memory")
; #define PG8_WAIT_L(n) asm volatile("s_waitcnt lgkmcnt(" #n ")" ::: "memory")
; #define PG8_BAR __builtin_amdgcn_s_barrier()
; #define PG8_SCHED __builtin_amdgcn_sched_barrier(0)
; template <class Epi, class Sched, bool ALIGN_EPI = false, bool SP2 = false, bool SPLITK = false>
; __device__ __forceinline__ void gemm_phase(PG8_LAS unsigned char* lds, const Gemm g, const Sched& S, const Epi& E) {
;     ...
;             PG8_WAIT_V(8); PG8_WAIT_L(0); PG8_BAR; PG8_MMA(0, 0, At, B0); PG8_MMA(0, 1, At, B1); PG8_BAR; PG8_SCHED;
;             PG8_LDA(At, 0, 1); PG8_STAGE(PG8_SB(0, 0), b2, voffB); PG8_STAGE(PG8_SB(0, 1), b2 + hstep, voffB); PG8_STAGE(PG8_SA(0, 0), a2, voffA);
;             PG8_WAIT_V(8); PG8_WAIT_L(0); PG8_BAR; PG8_MMA(1, 0, At, B0); PG8_MMA(1, 1, At, B1); PG8_BAR; PG8_SCHED;
	s_setprio 1
	s_waitcnt lgkmcnt(0)
	v_mfma_f32_16x16x32_bf16 v[126:129], v[130:133], v[162:165], v[126:129]
	v_mfma_f32_16x16x32_bf16 v[122:125], v[138:141], v[162:165], v[122:125]
	ds_read_b128 v[212:215], v199 offset:16384
	v_mfma_f32_16x16x32_bf16 v[114:117], v[130:133], v[182:185], v[114:117]
	v_mfma_f32_16x16x32_bf16 v[106:109], v[138:141], v[182:185], v[106:109]
	v_mfma_f32_16x16x32_bf16 v[98:101], v[130:133], v[190:193], v[98:101]
	v_mfma_f32_16x16x32_bf16 v[90:93], v[138:141], v[190:193], v[90:93]
	ds_read_b128 v[216:219], v199 offset:17408
	v_mfma_f32_16x16x32_bf16 v[82:85], v[130:133], v[204:207], v[82:85]
	v_mfma_f32_16x16x32_bf16 v[74:77], v[138:141], v[204:207], v[74:77]
	v_mfma_f32_16x16x32_bf16 v[126:129], v[134:137], v[178:181], v[126:129]
	v_mfma_f32_16x16x32_bf16 v[122:125], v[142:145], v[178:181], v[122:125]
	ds_read_b128 v[220:223], v199 offset:18432
	v_mfma_f32_16x16x32_bf16 v[114:117], v[134:137], v[186:189], v[114:117]
	v_mfma_f32_16x16x32_bf16 v[106:109], v[142:145], v[186:189], v[106:109]
	v_mfma_f32_16x16x32_bf16 v[98:101], v[134:137], v[200:203], v[98:101]
	v_mfma_f32_16x16x32_bf16 v[90:93], v[142:145], v[200:203], v[90:93]
	ds_read_b128 v[224:227], v199 offset:19456
	v_mfma_f32_16x16x32_bf16 v[82:85], v[134:137], v[208:211], v[82:85]
	v_mfma_f32_16x16x32_bf16 v[74:77], v[142:145], v[208:211], v[74:77]
	v_mfma_f32_16x16x32_bf16 v[118:121], v[146:149], v[162:165], v[118:121]
	v_mfma_f32_16x16x32_bf16 v[110:113], v[154:157], v[162:165], v[110:113]
	ds_read_b128 v[228:231], v199 offset:20480
	v_mfma_f32_16x16x32_bf16 v[102:105], v[146:149], v[182:185], v[102:105]
	v_mfma_f32_16x16x32_bf16 v[94:97], v[154:157], v[182:185], v[94:97]
	v_mfma_f32_16x16x32_bf16 v[86:89], v[146:149], v[190:193], v[86:89]
	v_mfma_f32_16x16x32_bf16 v[78:81], v[154:157], v[190:193], v[78:81]
	ds_read_b128 v[232:235], v199 offset:21504
	v_mfma_f32_16x16x32_bf16 v[70:73], v[146:149], v[204:207], v[70:73]
	v_mfma_f32_16x16x32_bf16 v[66:69], v[154:157], v[204:207], v[66:69]
	v_mfma_f32_16x16x32_bf16 v[118:121], v[150:153], v[178:181], v[118:121]
	v_mfma_f32_16x16x32_bf16 v[110:113], v[158:161], v[178:181], v[110:113]
	ds_read_b128 v[238:241], v199 offset:22528
	v_mfma_f32_16x16x32_bf16 v[102:105], v[150:153], v[186:189], v[102:105]
	v_mfma_f32_16x16x32_bf16 v[94:97], v[158:161], v[186:189], v[94:97]
	v_mfma_f32_16x16x32_bf16 v[86:89], v[150:153], v[200:203], v[86:89]
	v_mfma_f32_16x16x32_bf16 v[78:81], v[158:161], v[200:203], v[78:81]
	v_mfma_f32_16x16x32_bf16 v[70:73], v[150:153], v[208:211], v[70:73]
	v_mfma_f32_16x16x32_bf16 v[66:69], v[158:161], v[208:211], v[66:69]
	s_waitcnt vmcnt(2)
	s_setprio 0
	s_barrier
	s_add_i32 s43, s45, s33
	s_mov_b32 m0, s43
	ds_read_b128 v[208:211], v199 offset:23552
	global_load_lds_dwordx4 v0, s[46:47]
	s_add_i32 m0, s43, 0x2000
	s_add_u32 s76, s46, 0x40000
	s_addc_u32 s77, s47, 0
	s_add_i32 s35, s35, s33
	global_load_lds_dwordx4 v172, s[46:47]
	s_mov_b32 m0, s35
	s_nop 0
	global_load_lds_dwordx4 v0, s[76:77]
	s_add_i32 m0, s35, 0x2000
	s_nop 0
	global_load_lds_dwordx4 v172, s[76:77]
	s_mov_b32 m0, s51
	s_nop 0
	global_load_lds_dwordx4 v168, s[48:49]
	s_mov_b32 m0, s53
	s_nop 0
	global_load_lds_dwordx4 v170, s[48:49]
	s_waitcnt vmcnt(8)
	s_waitcnt lgkmcnt(0)
	s_barrier
	s_setprio 1
	s_waitcnt lgkmcnt(0)
	v_mfma_f32_16x16x32_bf16 v[62:65], v[130:133], v[212:215], v[62:65]
	v_mfma_f32_16x16x32_bf16 v[58:61], v[138:141], v[212:215], v[58:61]
	ds_read_b128 v[162:165], v199 offset:32768
	v_mfma_f32_16x16x32_bf16 v[50:53], v[130:133], v[220:223], v[50:53]
	v_mfma_f32_16x16x32_bf16 v[42:45], v[138:141], v[220:223], v[42:45]
	v_mfma_f32_16x16x32_bf16 v[34:37], v[130:133], v[228:231], v[34:37]
	v_mfma_f32_16x16x32_bf16 v[26:29], v[138:141], v[228:231], v[26:29]
	ds_read_b128 v[178:181], v199 offset:33792
	v_mfma_f32_16x16x32_bf16 v[18:21], v[130:133], v[238:241], v[18:21]
	v_mfma_f32_16x16x32_bf16 v[10:13], v[138:141], v[238:241], v[10:13]
	v_mfma_f32_16x16x32_bf16 v[62:65], v[134:137], v[216:219], v[62:65]
	v_mfma_f32_16x16x32_bf16 v[58:61], v[142:145], v[216:219], v[58:61]
	ds_read_b128 v[182:185], v199 offset:34816
	v_mfma_f32_16x16x32_bf16 v[50:53], v[134:137], v[224:227], v[50:53]
	v_mfma_f32_16x16x32_bf16 v[42:45], v[142:145], v[224:227], v[42:45]
	v_mfma_f32_16x16x32_bf16 v[34:37], v[134:137], v[232:235], v[34:37]
	v_mfma_f32_16x16x32_bf16 v[26:29], v[142:145], v[232:235], v[26:29]
	ds_read_b128 v[186:189], v199 offset:35840
	v_mfma_f32_16x16x32_bf16 v[18:21], v[134:137], v[208:211], v[18:21]
	v_mfma_f32_16x16x32_bf16 v[10:13], v[142:145], v[208:211], v[10:13]
	v_mfma_f32_16x16x32_bf16 v[54:57], v[146:149], v[212:215], v[54:57]
	v_mfma_f32_16x16x32_bf16 v[46:49], v[154:157], v[212:215], v[46:49]
	ds_read_b128 v[190:193], v199 offset:36864
	v_mfma_f32_16x16x32_bf16 v[38:41], v[146:149], v[220:223], v[38:41]
	v_mfma_f32_16x16x32_bf16 v[30:33], v[154:157], v[220:223], v[30:33]
	v_mfma_f32_16x16x32_bf16 v[22:25], v[146:149], v[228:231], v[22:25]
	v_mfma_f32_16x16x32_bf16 v[14:17], v[154:157], v[228:231], v[14:17]
	ds_read_b128 v[200:203], v199 offset:37888
	v_mfma_f32_16x16x32_bf16 v[6:9], v[146:149], v[238:241], v[6:9]
	v_mfma_f32_16x16x32_bf16 v[2:5], v[154:157], v[238:241], v[2:5]
	v_mfma_f32_16x16x32_bf16 v[54:57], v[150:153], v[216:219], v[54:57]
	v_mfma_f32_16x16x32_bf16 v[46:49], v[158:161], v[216:219], v[46:49]
	ds_read_b128 v[204:207], v199 offset:38912
	v_mfma_f32_16x16x32_bf16 v[38:41], v[150:153], v[224:227], v[38:41]
	v_mfma_f32_16x16x32_bf16 v[30:33], v[158:161], v[224:227], v[30:33]
	v_mfma_f32_16x16x32_bf16 v[22:25], v[150:153], v[232:235], v[22:25]
	v_mfma_f32_16x16x32_bf16 v[14:17], v[158:161], v[232:235], v[14:17]
	v_mfma_f32_16x16x32_bf16 v[6:9], v[150:153], v[208:211], v[6:9]
	v_mfma_f32_16x16x32_bf16 v[2:5], v[158:161], v[208:211], v[2:5]
	s_waitcnt vmcnt(6)
	s_setprio 0
	s_barrier
; #define PG8_STAGE(bufoff, gbase, voff) do { _Pragma("unroll") for (int _i = 0; _i < 2; ++_i) \
;         __builtin_amdgcn_global_load_lds((const unsigned*)((const char*)(gbase) + (voff)[_i]), (PG8_LAS unsigned*)(lds + (bufoff) + ldsw + _i * 8192), 16, 0, 0); } while (0)
; #define PG8_LDA(dst, b, h) do { _Pragma("unroll") for (int m = 0; m < 4; ++m) _Pragma("unroll") for (int k = 0; k < 2; ++k) dst[m][k] = *(const PG8_LAS bf16x8*)(lds + PG8_SA(b, h) + aoff + m * 2048 + k * 1024); } while (0)
; #define PG8_LDB(dst, b, h) do { _Pragma("unroll") for (int n = 0; n < 2; ++n) _Pragma("unroll") for (int k = 0; k < 2; ++k) dst[n][k] = *(const PG8_LAS bf16x8*)(lds + PG8_SB(b, h) + boff + n * 2048 + k * 1024); } while (0)
; #define PG8_MMA(ai, bj, At, Bt) do { __builtin_amdgcn_s_setprio(1); _Pragma("unroll") for (int m = 0; m < 4; ++m) _Pragma("unroll") for (int n = 0; n < 2; ++n) _Pragma("unroll") for (int k = 0; k < 2; ++k) \
;         acc[ai][bj][m][n] = __builtin_amdgcn_mfma_f32_16x16x32_bf16(Bt[n][k], At[m][k], acc[ai][bj][m][n], 0, 0, 0); __builtin_amdgcn_s_setprio(0); } while (0)
; #define PG8_WAIT_V(n) asm volatile("s_waitcnt vmcnt(" #n ")" ::: "memory")
; #define PG8_WAIT_L(n) asm volatile("s_waitcnt lgkmcnt(" #n ")" ::: "memory")
; #define PG8_BAR __builtin_amdgcn_s_barrier()
; #define PG8_SCHED __builtin_amdgcn_sched_barrier(0)
; template <class Epi, class Sched, bool ALIGN_EPI = false, bool SP2 = false, bool SPLITK = false>
; __device__ __forceinline__ void gemm_phase(PG8_LAS unsigned char* lds, const Gemm g, const Sched& S, const Epi& E) {
;     ...
;             PG8_LDB(B0, 1, 0); PG8_LDB(B1, 1, 1); PG8_SCHED; PG8_LDA(At, 1, 0); PG8_STAGE(PG8_SA(0, 1), a2 + hstep, voffA);
;             PG8_WAIT_V(8); PG8_WAIT_L(0); PG8_BAR; PG8_MMA(0, 0, At, B0); PG8_MMA(0, 1, At, B1); PG8_BAR; PG8_SCHED;
;             PG8_LDA(At, 1, 1); PG8_STAGE(PG8_SB(1, 0), b3, voffB); PG8_STAGE(PG8_SB(1, 1), b3 + hstep, voffB); PG8_STAGE(PG8_SA(1, 0), a3, voffA);
;             PG8_WAIT_V(8); PG8_WAIT_L(0); PG8_BAR; PG8_MMA(1, 0, At, B0); PG8_MMA(1, 1, At, B1); PG8_BAR; PG8_SCHED;
	s_add_i32 s35, 0, 0x18000
	s_add_i32 s43, 0, 0x1c000
	v_add_u32_e32 v142, s35, v198
	v_add_u32_e32 v158, s43, v198
	ds_read_b128 v[130:133], v142
	ds_read_b128 v[134:137], v142 offset:1024
	ds_read_b128 v[138:141], v142 offset:2048
	ds_read_b128 v[142:145], v142 offset:3072
	ds_read_b128 v[146:149], v158
	ds_read_b128 v[150:153], v158 offset:1024
	ds_read_b128 v[154:157], v158 offset:2048
	ds_read_b128 v[158:161], v158 offset:3072
	s_add_u32 s48, s48, 0x40000
	s_addc_u32 s49, s49, 0
	s_mov_b32 m0, s56
	ds_read_b128 v[208:211], v199 offset:39936
	global_load_lds_dwordx4 v168, s[48:49]
	s_mov_b32 m0, s57
	s_nop 0
	global_load_lds_dwordx4 v170, s[48:49]
	s_waitcnt vmcnt(8)
	s_waitcnt lgkmcnt(0)
	s_barrier
	s_setprio 1
	s_waitcnt lgkmcnt(0)
	v_mfma_f32_16x16x32_bf16 v[126:129], v[130:133], v[162:165], v[126:129]
	v_mfma_f32_16x16x32_bf16 v[122:125], v[138:141], v[162:165], v[122:125]
	ds_read_b128 v[212:215], v199 offset:49152
	v_mfma_f32_16x16x32_bf16 v[114:117], v[130:133], v[182:185], v[114:117]
	v_mfma_f32_16x16x32_bf16 v[106:109], v[138:141], v[182:185], v[106:109]
	v_mfma_f32_16x16x32_bf16 v[98:101], v[130:133], v[190:193], v[98:101]
	v_mfma_f32_16x16x32_bf16 v[90:93], v[138:141], v[190:193], v[90:93]
	ds_read_b128 v[216:219], v199 offset:50176
	v_mfma_f32_16x16x32_bf16 v[82:85], v[130:133], v[204:207], v[82:85]
	v_mfma_f32_16x16x32_bf16 v[74:77], v[138:141], v[204:207], v[74:77]
	v_mfma_f32_16x16x32_bf16 v[126:129], v[134:137], v[178:181], v[126:129]
	v_mfma_f32_16x16x32_bf16 v[122:125], v[142:145], v[178:181], v[122:125]
	ds_read_b128 v[220:223], v199 offset:51200
	v_mfma_f32_16x16x32_bf16 v[114:117], v[134:137], v[186:189], v[114:117]
	v_mfma_f32_16x16x32_bf16 v[106:109], v[142:145], v[186:189], v[106:109]
	v_mfma_f32_16x16x32_bf16 v[98:101], v[134:137], v[200:203], v[98:101]
	v_mfma_f32_16x16x32_bf16 v[90:93], v[142:145], v[200:203], v[90:93]
	ds_read_b128 v[224:227], v199 offset:52224
	v_mfma_f32_16x16x32_bf16 v[82:85], v[134:137], v[208:211], v[82:85]
	v_mfma_f32_16x16x32_bf16 v[74:77], v[142:145], v[208:211], v[74:77]
	v_mfma_f32_16x16x32_bf16 v[118:121], v[146:149], v[162:165], v[118:121]
	v_mfma_f32_16x16x32_bf16 v[110:113], v[154:157], v[162:165], v[110:113]
	ds_read_b128 v[228:231], v199 offset:53248
	v_mfma_f32_16x16x32_bf16 v[102:105], v[146:149], v[182:185], v[102:105]
	v_mfma_f32_16x16x32_bf16 v[94:97], v[154:157], v[182:185], v[94:97]
	v_mfma_f32_16x16x32_bf16 v[86:89], v[146:149], v[190:193], v[86:89]
	v_mfma_f32_16x16x32_bf16 v[78:81], v[154:157], v[190:193], v[78:81]
	ds_read_b128 v[232:235], v199 offset:54272
	v_mfma_f32_16x16x32_bf16 v[70:73], v[146:149], v[204:207], v[70:73]
	v_mfma_f32_16x16x32_bf16 v[66:69], v[154:157], v[204:207], v[66:69]
	v_mfma_f32_16x16x32_bf16 v[118:121], v[150:153], v[178:181], v[118:121]
	v_mfma_f32_16x16x32_bf16 v[110:113], v[158:161], v[178:181], v[110:113]
	ds_read_b128 v[238:241], v199 offset:55296
	v_mfma_f32_16x16x32_bf16 v[102:105], v[150:153], v[186:189], v[102:105]
	v_mfma_f32_16x16x32_bf16 v[94:97], v[158:161], v[186:189], v[94:97]
	v_mfma_f32_16x16x32_bf16 v[86:89], v[150:153], v[200:203], v[86:89]
	v_mfma_f32_16x16x32_bf16 v[78:81], v[158:161], v[200:203], v[78:81]
	v_mfma_f32_16x16x32_bf16 v[70:73], v[150:153], v[208:211], v[70:73]
	v_mfma_f32_16x16x32_bf16 v[66:69], v[158:161], v[208:211], v[66:69]
	s_waitcnt vmcnt(2)
	s_setprio 0
	s_barrier
	s_add_i32 s35, s35, s33
	s_add_u32 s46, s46, 0x80
	s_addc_u32 s47, s47, 0
	s_mov_b32 m0, s35
	ds_read_b128 v[208:211], v199 offset:56320
	global_load_lds_dwordx4 v0, s[46:47]
	s_add_i32 m0, s35, 0x2000
	s_add_i32 s35, s43, s33
	global_load_lds_dwordx4 v172, s[46:47]
	s_add_u32 s46, s46, 0x40000
	s_addc_u32 s47, s47, 0
	s_mov_b32 m0, s35
	s_nop 0
	global_load_lds_dwordx4 v0, s[46:47]
	s_add_i32 m0, s35, 0x2000
	s_nop 0
	global_load_lds_dwordx4 v172, s[46:47]
	s_sub_u32 s76, s48, 0x3ff80
	s_subb_u32 s77, s49, 0
	s_mov_b32 m0, s58
	s_nop 0
	global_load_lds_dwordx4 v168, s[76:77]
	s_mov_b32 m0, s59
	s_nop 0
	global_load_lds_dwordx4 v170, s[76:77]
	s_waitcnt vmcnt(8)
	s_waitcnt lgkmcnt(0)
	s_barrier
	s_setprio 1
	s_waitcnt lgkmcnt(0)
	v_mfma_f32_16x16x32_bf16 v[62:65], v[130:133], v[212:215], v[62:65]
	v_mfma_f32_16x16x32_bf16 v[58:61], v[138:141], v[212:215], v[58:61]
	ds_read_b128 v[162:165], v199 offset:0
	v_mfma_f32_16x16x32_bf16 v[50:53], v[130:133], v[220:223], v[50:53]
	v_mfma_f32_16x16x32_bf16 v[42:45], v[138:141], v[220:223], v[42:45]
	v_mfma_f32_16x16x32_bf16 v[34:37], v[130:133], v[228:231], v[34:37]
	v_mfma_f32_16x16x32_bf16 v[26:29], v[138:141], v[228:231], v[26:29]
	ds_read_b128 v[178:181], v199 offset:1024
	v_mfma_f32_16x16x32_bf16 v[18:21], v[130:133], v[238:241], v[18:21]
	v_mfma_f32_16x16x32_bf16 v[10:13], v[138:141], v[238:241], v[10:13]
	v_mfma_f32_16x16x32_bf16 v[62:65], v[134:137], v[216:219], v[62:65]
	v_mfma_f32_16x16x32_bf16 v[58:61], v[142:145], v[216:219], v[58:61]
	ds_read_b128 v[182:185], v199 offset:2048
	v_mfma_f32_16x16x32_bf16 v[50:53], v[134:137], v[224:227], v[50:53]
	v_mfma_f32_16x16x32_bf16 v[42:45], v[142:145], v[224:227], v[42:45]
	v_mfma_f32_16x16x32_bf16 v[34:37], v[134:137], v[232:235], v[34:37]
	v_mfma_f32_16x16x32_bf16 v[26:29], v[142:145], v[232:235], v[26:29]
	ds_read_b128 v[186:189], v199 offset:3072
	v_mfma_f32_16x16x32_bf16 v[18:21], v[134:137], v[208:211], v[18:21]
	v_mfma_f32_16x16x32_bf16 v[10:13], v[142:145], v[208:211], v[10:13]
	v_mfma_f32_16x16x32_bf16 v[54:57], v[146:149], v[212:215], v[54:57]
	v_mfma_f32_16x16x32_bf16 v[46:49], v[154:157], v[212:215], v[46:49]
	ds_read_b128 v[190:193], v199 offset:4096
	v_mfma_f32_16x16x32_bf16 v[38:41], v[146:149], v[220:223], v[38:41]
	v_mfma_f32_16x16x32_bf16 v[30:33], v[154:157], v[220:223], v[30:33]
	v_mfma_f32_16x16x32_bf16 v[22:25], v[146:149], v[228:231], v[22:25]
	v_mfma_f32_16x16x32_bf16 v[14:17], v[154:157], v[228:231], v[14:17]
	ds_read_b128 v[200:203], v199 offset:5120
	v_mfma_f32_16x16x32_bf16 v[6:9], v[146:149], v[238:241], v[6:9]
	v_mfma_f32_16x16x32_bf16 v[2:5], v[154:157], v[238:241], v[2:5]
	v_mfma_f32_16x16x32_bf16 v[54:57], v[150:153], v[216:219], v[54:57]
	v_mfma_f32_16x16x32_bf16 v[46:49], v[158:161], v[216:219], v[46:49]
	ds_read_b128 v[204:207], v199 offset:6144
	v_mfma_f32_16x16x32_bf16 v[38:41], v[150:153], v[224:227], v[38:41]
	v_mfma_f32_16x16x32_bf16 v[30:33], v[158:161], v[224:227], v[30:33]
	v_mfma_f32_16x16x32_bf16 v[22:25], v[150:153], v[232:235], v[22:25]
	v_mfma_f32_16x16x32_bf16 v[14:17], v[158:161], v[232:235], v[14:17]
	v_mfma_f32_16x16x32_bf16 v[6:9], v[150:153], v[208:211], v[6:9]
	v_mfma_f32_16x16x32_bf16 v[2:5], v[158:161], v[208:211], v[2:5]
	s_waitcnt vmcnt(6)
	s_setprio 0
	s_barrier
	s_add_i32 s25, s25, 2
	s_add_u32 s54, s54, 0x100
	s_addc_u32 s55, s55, 0
	s_add_u32 s23, s23, 0x100
	s_addc_u32 s24, s24, 0
	s_cmp_gt_u32 s25, 13
	s_cbranch_scc0 .LBB0_165
	s_waitcnt lgkmcnt(0)
	v_mov_b64_e32 v[230:231], 0xff
	v_mov_b32_e32 v234, 1
	v_mov_b32_e32 v235, 0x3e38aa3b
	s_and_b64 vcc, exec, s[16:17]
	s_cbranch_vccz .LBB0_168
	s_barrier
